# ssd: stagger prefetch for waves 4-7, hw exp2/log2 softplus, DPP scans, batched G/y_diag LDS reads, counted vmcnt
# speedup vs baseline: 1.0134x; 1.0097x over previous
; __device__ __forceinline__ float wave_incl_scan(float v, int lane) {
; #pragma unroll
;     for (int o = 1; o < 64; o <<= 1) { const float t = __int_as_float(__builtin_amdgcn_ds_bpermute(((lane - o) & 63) << 2, __float_as_int(v))); if (lane >= o) v += t; }
;     return v;
; }
.LBB0_409:
	v_mul_f32_e64 v73, v2, -v213
	v_mul_f32_e64 v74, v72, -v213
	s_xor_b32 s18, s94, 0x80
	s_lshl_b32 s18, s18, 2
	s_add_i32 s18, s18, 0
	s_add_i32 s26, s18, 0x1e400
	s_add_i32 s19, s18, 0x1e800
	s_add_i32 s18, s18, 0x1ec00
	v_add_u32_e32 v76, s19, v220
	s_nop 0
	v_add_f32_dpp v73, v73, v73 row_shr:1 row_mask:0xf bank_mask:0xf
	v_add_f32_dpp v74, v74, v74 row_shr:1 row_mask:0xf bank_mask:0xf
	s_nop 0
	v_add_f32_dpp v73, v73, v73 row_shr:2 row_mask:0xf bank_mask:0xf
	v_add_f32_dpp v74, v74, v74 row_shr:2 row_mask:0xf bank_mask:0xf
	s_nop 0
	v_add_f32_dpp v73, v73, v73 row_shr:4 row_mask:0xf bank_mask:0xf
	v_add_f32_dpp v74, v74, v74 row_shr:4 row_mask:0xf bank_mask:0xf
	s_nop 0
	v_add_f32_dpp v73, v73, v73 row_shr:8 row_mask:0xf bank_mask:0xf
	v_add_f32_dpp v74, v74, v74 row_shr:8 row_mask:0xf bank_mask:0xf
	s_nop 0
	v_add_f32_dpp v73, v73, v73 row_bcast:15 row_mask:0xa bank_mask:0xf
	v_add_f32_dpp v74, v74, v74 row_bcast:15 row_mask:0xa bank_mask:0xf
	s_nop 0
	v_add_f32_dpp v73, v73, v73 row_bcast:31 row_mask:0xc bank_mask:0xf
	v_add_f32_dpp v74, v74, v74 row_bcast:31 row_mask:0xc bank_mask:0xf
	s_nop 1
	v_readlane_b32 s27, v73, 63
	s_nop 1
	v_add_f32_e32 v74, s27, v74
	v_add_u32_e32 v75, s26, v220
	v_readlane_b32 s27, v74, 63
	ds_write_b32 v75, v2
	v_add_u32_e32 v75, s26, v242
	ds_write_b32 v75, v72
	v_mul_f32_e32 v75, 0x3fb8aa3b, v73
	v_sub_f32_e32 v73, s27, v73
	v_mul_f32_e32 v73, 0x3fb8aa3b, v73
	v_exp_f32_e32 v73, v73
	ds_write_b32 v76, v75
	v_mul_f32_e32 v75, 0x3fb8aa3b, v74
	v_add_u32_e32 v76, s19, v242
	v_mul_f32_e32 v2, v2, v73
	v_add_u32_e32 v73, s18, v220
	ds_write_b32 v76, v75
	ds_write_b32 v73, v2
	v_sub_f32_e32 v2, s27, v74
	v_mul_f32_e32 v2, 0x3fb8aa3b, v2
	v_exp_f32_e32 v2, v2
	s_nop 0
	v_mul_f32_e32 v2, v72, v2
	v_add_u32_e32 v72, s18, v242
	ds_write_b32 v72, v2

; __device__ __forceinline__ unsigned cvt_pk_bf16(float lo, float hi) { unsigned r; asm volatile("v_cvt_pk_bf16_f32 %0, %1, %2" : "=v"(r) : "v"(lo), "v"(hi)); return r; }
; __device__ __forceinline__ float bflo(unsigned u) { return __uint_as_float(u << 16); }
; template <int VAR, bool SIDE> ...
;     ...
;         f32x4 o2[2][2];
;         { const f32x4 ba = *(const LAS f32x4*)(cwt + 256 + xch * 8), bb = *(const LAS f32x4*)(cwt + 256 + xch * 8 + 4); o2[0][0] = ba; o2[0][1] = bb; o2[1][0] = ba; o2[1][1] = bb; }
; #pragma unroll
;         for (int j = 0; j < 4; ++j) { const f32x4 wa = *(const LAS f32x4*)(cwt + j * 64 + xch * 8), wb = *(const LAS f32x4*)(cwt + j * 64 + xch * 8 + 4);
; #pragma unroll
;             for (int rr = 0; rr < 2; ++rr) { const u32x4 rv = xraw[rr + j];
;                 o2[rr][0] += (f32x4){bflo(rv.x), bfhi(rv.x), bflo(rv.y), bfhi(rv.y)} * wa; o2[rr][1] += (f32x4){bflo(rv.z), bfhi(rv.z), bflo(rv.w), bfhi(rv.w)} * wb; } }
;         { f32x4 t[2][2];
; #pragma unroll
;             for (int rr = 0; rr < 2; ++rr)
; #pragma unroll
;                 for (int hq = 0; hq < 2; ++hq)
;                     { const f32x4 ta = o2[rr][hq] * -1.4426950408889634f;
; #pragma unroll
;                       for (int e = 0; e < 4; ++e) t[rr][hq][e] = __builtin_amdgcn_exp2f(ta[e]); }
; #pragma unroll
;             for (int rr = 0; rr < 2; ++rr)
; #pragma unroll
;                 for (int hq = 0; hq < 2; ++hq)
;                     { const f32x4 tb = t[rr][hq] + 1.0f;
; #pragma unroll
;                       for (int e = 0; e < 4; ++e) t[rr][hq][e] = __builtin_amdgcn_rcpf(tb[e]); }
; #pragma unroll
;             for (int rr = 0; rr < 2; ++rr)
; #pragma unroll
;                 for (int hq = 0; hq < 2; ++hq) o2[rr][hq] = o2[rr][hq] * t[rr][hq]; }
; #pragma unroll
;         for (int rr = 0; rr < 2; ++rr) { const f32x4 oa = o2[rr][0], ob = o2[rr][1];
;             u32x4 w; w.x = cvt_pk_bf16(oa[0], oa[1]); w.y = cvt_pk_bf16(oa[2], oa[3]); w.z = cvt_pk_bf16(ob[0], ob[1]); w.w = cvt_pk_bf16(ob[2], ob[3]);
;             *(LAS u32x4*)(Xs + (xr0 + rr) * XS + xch * 16) = w;
;             const float f = wl[xr0 + rr]; const f32x4 pa = oa * f, pb = ob * f;
;             w.x = cvt_pk_bf16(pa[0], pa[1]); w.y = cvt_pk_bf16(pa[2], pa[3]); w.z = cvt_pk_bf16(pb[0], pb[1]); w.w = cvt_pk_bf16(pb[2], pb[3]);
;             *(LAS u32x4*)(Xw + (xr0 + rr) * XS + xch * 16) = w; }
.LBB0_411:
	ds_read_b128 v[72:75], v221
	ds_read_b128 v[76:79], v221 offset:16
	ds_read_b128 v[80:83], v222
	ds_read_b128 v[84:87], v222 offset:16
	v_lshlrev_b32_e32 v88, 16, v8
	v_and_b32_e32 v89, 0xffff0000, v8
	v_lshlrev_b32_e32 v90, 16, v9
	v_and_b32_e32 v91, 0xffff0000, v9
	v_lshlrev_b32_e32 v92, 16, v10
	v_and_b32_e32 v93, 0xffff0000, v10
	v_lshlrev_b32_e32 v94, 16, v11
	v_and_b32_e32 v95, 0xffff0000, v11
	v_lshlrev_b32_e32 v96, 16, v4
	v_and_b32_e32 v97, 0xffff0000, v4
	v_lshlrev_b32_e32 v98, 16, v5
	v_and_b32_e32 v99, 0xffff0000, v5
	v_lshlrev_b32_e32 v100, 16, v6
	v_and_b32_e32 v101, 0xffff0000, v6
	v_lshlrev_b32_e32 v102, 16, v7
	v_and_b32_e32 v103, 0xffff0000, v7
	s_waitcnt lgkmcnt(0)
	v_pk_fma_f32 v[88:89], v[80:81], v[88:89], v[72:73]
	v_pk_fma_f32 v[90:91], v[82:83], v[90:91], v[74:75]
	v_pk_fma_f32 v[92:93], v[84:85], v[92:93], v[76:77]
	v_pk_fma_f32 v[94:95], v[86:87], v[94:95], v[78:79]
	v_pk_fma_f32 v[80:81], v[80:81], v[96:97], v[72:73]
	v_pk_fma_f32 v[82:83], v[82:83], v[98:99], v[74:75]
	v_pk_fma_f32 v[84:85], v[84:85], v[100:101], v[76:77]
	v_pk_fma_f32 v[86:87], v[86:87], v[102:103], v[78:79]
	ds_read_b128 v[72:75], v222 offset:256
	ds_read_b128 v[76:79], v222 offset:272
	s_and_b32 s94, s95, 0x80
	s_lshl_b32 s46, s94, 2
	s_add_i32 s33, s46, 0
	s_waitcnt lgkmcnt(0)
	v_pk_fma_f32 v[90:91], v[74:75], v[98:99], v[90:91]
	v_pk_fma_f32 v[88:89], v[72:73], v[96:97], v[88:89]
	v_pk_fma_f32 v[94:95], v[78:79], v[102:103], v[94:95]
	v_pk_fma_f32 v[92:93], v[76:77], v[100:101], v[92:93]
	v_lshlrev_b32_e32 v96, 16, v12
	v_and_b32_e32 v97, 0xffff0000, v12
	v_lshlrev_b32_e32 v98, 16, v13
	v_and_b32_e32 v99, 0xffff0000, v13
	v_lshlrev_b32_e32 v100, 16, v14
	v_and_b32_e32 v101, 0xffff0000, v14
	v_lshlrev_b32_e32 v102, 16, v15
	v_and_b32_e32 v103, 0xffff0000, v15
	v_pk_fma_f32 v[82:83], v[74:75], v[98:99], v[82:83]
	v_pk_fma_f32 v[80:81], v[72:73], v[96:97], v[80:81]
	v_pk_fma_f32 v[86:87], v[78:79], v[102:103], v[86:87]
	v_pk_fma_f32 v[84:85], v[76:77], v[100:101], v[84:85]
	ds_read_b128 v[72:75], v222 offset:512
	ds_read_b128 v[76:79], v222 offset:528
	s_add_i32 s18, s33, 0x1ec00
	s_cmpk_eq_i32 s95, 0xf80
	s_waitcnt lgkmcnt(0)
	v_pk_fma_f32 v[88:89], v[72:73], v[96:97], v[88:89]
	v_pk_fma_f32 v[90:91], v[74:75], v[98:99], v[90:91]
	v_pk_fma_f32 v[92:93], v[76:77], v[100:101], v[92:93]
	v_pk_fma_f32 v[94:95], v[78:79], v[102:103], v[94:95]
	v_lshlrev_b32_e32 v96, 16, v16
	v_and_b32_e32 v97, 0xffff0000, v16
	v_lshlrev_b32_e32 v98, 16, v17
	v_and_b32_e32 v99, 0xffff0000, v17
	v_lshlrev_b32_e32 v100, 16, v18
	v_and_b32_e32 v101, 0xffff0000, v18
	v_lshlrev_b32_e32 v102, 16, v19
	v_and_b32_e32 v103, 0xffff0000, v19
	v_pk_fma_f32 v[80:81], v[72:73], v[96:97], v[80:81]
	v_pk_fma_f32 v[82:83], v[74:75], v[98:99], v[82:83]
	v_pk_fma_f32 v[84:85], v[76:77], v[100:101], v[84:85]
	v_pk_fma_f32 v[86:87], v[78:79], v[102:103], v[86:87]
	ds_read_b128 v[72:75], v222 offset:768
	ds_read_b128 v[76:79], v222 offset:784
	s_waitcnt lgkmcnt(0)
	v_pk_fma_f32 v[88:89], v[72:73], v[96:97], v[88:89]
	v_lshlrev_b32_e32 v96, 16, v20
	v_and_b32_e32 v97, 0xffff0000, v20
	v_pk_fma_f32 v[72:73], v[72:73], v[96:97], v[80:81]
	v_lshlrev_b32_e32 v80, 16, v22
	v_and_b32_e32 v81, 0xffff0000, v22
	v_pk_fma_f32 v[90:91], v[74:75], v[98:99], v[90:91]
	v_pk_fma_f32 v[92:93], v[76:77], v[100:101], v[92:93]
	v_lshlrev_b32_e32 v98, 16, v21
	v_and_b32_e32 v99, 0xffff0000, v21
	v_pk_fma_f32 v[76:77], v[76:77], v[80:81], v[84:85]
	v_mul_f32_e32 v80, 0xbfb8aa3b, v89
	v_pk_fma_f32 v[74:75], v[74:75], v[98:99], v[82:83]
	v_lshlrev_b32_e32 v82, 16, v23
	v_and_b32_e32 v83, 0xffff0000, v23
	v_exp_f32_e32 v81, v80
	v_mul_f32_e32 v80, 0xbfb8aa3b, v90
	v_pk_fma_f32 v[94:95], v[78:79], v[102:103], v[94:95]
	v_pk_fma_f32 v[78:79], v[78:79], v[82:83], v[86:87]
	v_exp_f32_e32 v82, v80
	v_mul_f32_e32 v80, 0xbfb8aa3b, v91
	v_exp_f32_e32 v83, v80
	v_mul_f32_e32 v80, 0xbfb8aa3b, v92
	v_exp_f32_e32 v84, v80
	v_mul_f32_e32 v80, 0xbfb8aa3b, v93
	v_exp_f32_e32 v85, v80
	v_mul_f32_e32 v80, 0xbfb8aa3b, v94
	v_exp_f32_e32 v86, v80
	v_mul_f32_e32 v80, 0xbfb8aa3b, v95
	v_exp_f32_e32 v87, v80
	v_mul_f32_e32 v80, 0xbfb8aa3b, v72
	v_exp_f32_e32 v96, v80
	v_mul_f32_e32 v80, 0xbfb8aa3b, v73
	v_mul_f32_e32 v2, 0xbfb8aa3b, v88
	v_exp_f32_e32 v97, v80
	v_mul_f32_e32 v80, 0xbfb8aa3b, v74
	v_exp_f32_e32 v2, v2
	v_exp_f32_e32 v98, v80
	v_mul_f32_e32 v80, 0xbfb8aa3b, v75
	v_exp_f32_e32 v99, v80
	v_mul_f32_e32 v80, 0xbfb8aa3b, v76
	v_exp_f32_e32 v100, v80
	v_mul_f32_e32 v80, 0xbfb8aa3b, v77
	v_exp_f32_e32 v101, v80
	v_mul_f32_e32 v80, 0xbfb8aa3b, v78
	v_exp_f32_e32 v102, v80
	v_mul_f32_e32 v80, 0xbfb8aa3b, v79
	v_add_f32_e32 v2, 1.0, v2
	v_exp_f32_e32 v103, v80
	v_rcp_f32_e32 v80, v2
	v_add_f32_e32 v2, 1.0, v81
	v_rcp_f32_e32 v81, v2
	v_add_f32_e32 v2, 1.0, v82
	v_rcp_f32_e32 v82, v2
	v_add_f32_e32 v2, 1.0, v83
	v_rcp_f32_e32 v83, v2
	v_add_f32_e32 v2, 1.0, v84
	v_rcp_f32_e32 v84, v2
	v_add_f32_e32 v2, 1.0, v85
	v_rcp_f32_e32 v85, v2
	v_add_f32_e32 v2, 1.0, v86
	v_rcp_f32_e32 v86, v2
	v_add_f32_e32 v2, 1.0, v87
	v_rcp_f32_e32 v87, v2
	v_add_f32_e32 v2, 1.0, v96
	v_rcp_f32_e32 v96, v2
	v_add_f32_e32 v2, 1.0, v97
	v_rcp_f32_e32 v97, v2
	v_add_f32_e32 v2, 1.0, v98
	v_rcp_f32_e32 v98, v2
	v_add_f32_e32 v2, 1.0, v99
	v_rcp_f32_e32 v99, v2
	v_add_f32_e32 v2, 1.0, v100
	v_rcp_f32_e32 v100, v2
	v_add_f32_e32 v2, 1.0, v101
	v_rcp_f32_e32 v101, v2
	v_add_f32_e32 v2, 1.0, v102
	v_rcp_f32_e32 v102, v2
	v_add_f32_e32 v2, 1.0, v103
	v_rcp_f32_e32 v103, v2
	v_pk_mul_f32 v[82:83], v[90:91], v[82:83]
	v_pk_mul_f32 v[80:81], v[88:89], v[80:81]
	v_pk_mul_f32 v[86:87], v[94:95], v[86:87]
	v_pk_mul_f32 v[84:85], v[92:93], v[84:85]
	v_pk_mul_f32 v[88:89], v[74:75], v[98:99]
	v_pk_mul_f32 v[90:91], v[72:73], v[96:97]
	v_cvt_pk_bf16_f32 v72, v80, v81
	v_cvt_pk_bf16_f32 v73, v82, v83
	v_cvt_pk_bf16_f32 v74, v84, v85
	v_cvt_pk_bf16_f32 v75, v86, v87
	ds_write_b128 v236, v[72:75]
	v_lshl_add_u32 v2, v201, 2, s18
	ds_read_b32 v2, v2
	v_pk_mul_f32 v[78:79], v[78:79], v[102:103]
	v_pk_mul_f32 v[76:77], v[76:77], v[100:101]
	s_waitcnt lgkmcnt(0)
; #define LAS __attribute__((address_space(3)))
; #define LDS_BARRIER() asm volatile("s_waitcnt lgkmcnt(0)\n\ts_barrier" ::: "memory")
; template <int VAR, bool SIDE> ...
;     ...
;         for (int i = 0; i < 8; ++i) *(LAS u32x4*)(bcdst + 16 * i * BS) = bcraw[i];
;         if (SIDE) { side_drain(sd0, sv0); sd0.mode = 0; }
;         LDS_BARRIER();
;         if (c + 1 < 32 && !(VAR & 2)) SSD_LOADS(c + 1);
;         {
;             const int lt = wave < 4 ? wave : 11 - wave;
;             const int l = 16 * lt + l15; const float acl = acum[l];
;             const size_t token = (size_t)(tok0 + l);
;             bf16_t* zp = P + token * NPROJ + COL_Z + hd * 64 + 4 * q4;
;             u32x2 zv[4];
; #pragma unroll
;             for (int pt = 0; pt < 4; ++pt) { zv[pt] = (u32x2){0x3f803f80u, 0x3f803f80u}; if (!(VAR & 1)) zv[pt] = *(const u32x2*)(zp + 16 * pt); }
	v_pk_mul_f32 v[74:75], v[2:3], v[82:83] op_sel_hi:[0,1]
	v_pk_mul_f32 v[72:73], v[2:3], v[80:81] op_sel_hi:[0,1]
	v_pk_mul_f32 v[80:81], v[2:3], v[86:87] op_sel_hi:[0,1]
	v_pk_mul_f32 v[82:83], v[2:3], v[84:85] op_sel_hi:[0,1]
	v_cvt_pk_bf16_f32 v72, v72, v73
	v_cvt_pk_bf16_f32 v73, v74, v75
	v_cvt_pk_bf16_f32 v74, v82, v83
	v_cvt_pk_bf16_f32 v75, v80, v81
	ds_write_b128 v236, v[72:75] offset:18432
	v_cvt_pk_bf16_f32 v72, v90, v91
	v_cvt_pk_bf16_f32 v73, v88, v89
	v_cvt_pk_bf16_f32 v74, v76, v77
	v_cvt_pk_bf16_f32 v75, v78, v79
	ds_write_b128 v237, v[72:75]
	v_lshl_add_u32 v2, v231, 2, s18
	ds_read_b32 v2, v2
	s_cselect_b64 s[18:19], -1, 0
	s_cmpk_lg_i32 s95, 0xf80
	s_cselect_b64 s[26:27], -1, 0
	s_and_b64 vcc, exec, s[18:19]
	s_waitcnt lgkmcnt(0)
	v_pk_mul_f32 v[74:75], v[88:89], v[2:3] op_sel_hi:[1,0]
	v_pk_mul_f32 v[72:73], v[90:91], v[2:3] op_sel_hi:[1,0]
	v_pk_mul_f32 v[78:79], v[78:79], v[2:3] op_sel_hi:[1,0]
	v_pk_mul_f32 v[76:77], v[76:77], v[2:3] op_sel_hi:[1,0]
	v_cvt_pk_bf16_f32 v72, v72, v73
	v_cvt_pk_bf16_f32 v73, v74, v75
	s_nop 0
	v_cvt_pk_bf16_f32 v74, v76, v77
	v_cvt_pk_bf16_f32 v75, v78, v79
	ds_write_b128 v237, v[72:75] offset:18432
	s_waitcnt vmcnt(0)
	ds_write_b128 v238, v[24:27]
	ds_write_b128 v238, v[28:31] offset:4352
	ds_write_b128 v238, v[32:35] offset:8704
	ds_write_b128 v238, v[36:39] offset:13056
	ds_write_b128 v238, v[40:43] offset:17408
	ds_write_b128 v238, v[44:47] offset:21760
	s_waitcnt vmcnt(0)
	ds_write_b128 v238, v[48:51] offset:26112
	ds_write_b128 v238, v[52:55] offset:30464
	s_waitcnt lgkmcnt(0)
	s_barrier
	s_cmp_ge_u32 s83, 0x100
	s_cbranch_scc1 .Lssd_late_pf
	s_cbranch_vccnz .LBB0_414
	v_add_u32_e32 v2, s95, v234
	v_add_u32_e32 v4, 0x7d, v2
	v_mov_b64_e32 v[20:21], s[66:67]
	v_mad_i64_i32 v[4:5], s[48:49], v4, s69, v[20:21]
	v_mov_b32_e32 v107, v3
	v_lshl_add_u64 v[4:5], v[4:5], 0, v[106:107]
	v_add_u32_e32 v6, 0x7e, v2
	v_add_co_u32_e32 v4, vcc, 0x4000, v4
	v_mad_i64_i32 v[6:7], s[48:49], v6, s69, v[20:21]
	s_nop 0
	v_addc_co_u32_e32 v5, vcc, 0, v5, vcc
	v_lshl_add_u64 v[6:7], v[6:7], 0, v[106:107]
	v_add_u32_e32 v12, 0x7f, v2
	v_add_co_u32_e32 v6, vcc, 0x4000, v6
	v_mad_i64_i32 v[12:13], s[48:49], v12, s69, v[20:21]
	s_nop 0
	v_addc_co_u32_e32 v7, vcc, 0, v7, vcc
	v_lshl_add_u64 v[12:13], v[12:13], 0, v[106:107]
	v_add_u32_e32 v14, 0x80, v2
	v_add_co_u32_e32 v12, vcc, 0x4000, v12
	v_mad_i64_i32 v[14:15], s[48:49], v14, s69, v[20:21]
	s_nop 0
	v_addc_co_u32_e32 v13, vcc, 0, v13, vcc
	v_lshl_add_u64 v[14:15], v[14:15], 0, v[106:107]
	v_add_u32_e32 v2, 0x81, v2
	v_add_co_u32_e32 v16, vcc, 0x4000, v14
	v_mad_i64_i32 v[20:21], s[48:49], v2, s69, v[20:21]
	s_nop 0
	v_addc_co_u32_e32 v17, vcc, 0, v15, vcc
	v_lshl_add_u64 v[20:21], v[20:21], 0, v[106:107]
	v_add_co_u32_e32 v20, vcc, 0x4000, v20
	global_load_dwordx4 v[8:11], v[4:5], off offset:1024
	s_nop 0
	global_load_dwordx4 v[4:7], v[6:7], off offset:1024
	v_addc_co_u32_e32 v21, vcc, 0, v21, vcc
	global_load_dwordx4 v[12:15], v[12:13], off offset:1024
	s_nop 0
	global_load_dwordx4 v[16:19], v[16:17], off offset:1024
	s_andn2_b64 vcc, exec, s[0:1]
	global_load_dwordx4 v[20:23], v[20:21], off offset:1024
	s_cbranch_vccnz .LBB0_414
	v_add_u32_e32 v2, s95, v233
	v_add_u32_e32 v72, 0x80, v2
	v_ashrrev_i32_e32 v73, 31, v72
	v_lshlrev_b64 v[72:73], 8, v[72:73]
	v_lshl_add_u64 v[72:73], s[6:7], 0, v[72:73]
	global_load_dword v211, v[72:73], off
	v_add_u32_e32 v72, 0xc0, v2
	v_ashrrev_i32_e32 v73, 31, v72
	v_lshlrev_b64 v[72:73], 8, v[72:73]
	v_lshl_add_u64 v[72:73], s[6:7], 0, v[72:73]
	global_load_dword v212, v[72:73], off
.LBB0_414:
	s_add_i32 s33, s33, 0x1e800
	v_lshl_add_u32 v2, v223, 2, s33
	ds_read_b32 v105, v2
	v_add_u32_e32 v2, s95, v235
	v_mov_b64_e32 v[72:73], s[66:67]
	v_mad_i64_i32 v[72:73], s[48:49], v2, s69, v[72:73]
	v_lshl_add_u64 v[72:73], v[72:73], 0, s[30:31]
	v_lshlrev_b32_e32 v2, 1, v108
	v_lshl_add_u64 v[72:73], v[72:73], 0, v[2:3]
	s_mov_b64 s[48:49], 0x2400
	v_lshl_add_u64 v[144:145], v[72:73], 0, s[48:49]
	v_add_co_u32_e32 v72, vcc, s70, v72
	s_nop 1
	v_addc_co_u32_e32 v73, vcc, 0, v73, vcc
	global_load_dwordx2 v[152:153], v[72:73], off offset:1024
	global_load_dwordx2 v[150:151], v[144:145], off offset:32
	global_load_dwordx2 v[148:149], v[144:145], off offset:64
	global_load_dwordx2 v[146:147], v[144:145], off offset:96
	s_branch .Lssd_yoff
; #define LAS __attribute__((address_space(3)))
; __device__ __forceinline__ f32x4 mfma16(bf16x8 a, bf16x8 b, f32x4 c) { return __builtin_amdgcn_mfma_f32_16x16x32_bf16(a, b, c, 0, 0, 0); }
; template <int VAR, bool SIDE> ...
;     ...
;         if (c + 1 < 32 && !(VAR & 2)) SSD_LOADS(c + 1);
;         {
;             const int lt = wave < 4 ? wave : 11 - wave;
;             const int l = 16 * lt + l15; const float acl = acum[l];
;             const size_t token = (size_t)(tok0 + l);
;             bf16_t* zp = P + token * NPROJ + COL_Z + hd * 64 + 4 * q4;
;             u32x2 zv[4];
; #pragma unroll
;             for (int pt = 0; pt < 4; ++pt) { zv[pt] = (u32x2){0x3f803f80u, 0x3f803f80u}; if (!(VAR & 1)) zv[pt] = *(const u32x2*)(zp + 16 * pt); }
;             f32x4 Y[4];
; #pragma unroll
;             for (int pt = 0; pt < 4; ++pt) Y[pt] = (f32x4){0.f, 0.f, 0.f, 0.f};
;             bf16x8 Cf[4];
;             LAS unsigned char* cbase = Cm + l * BS + q4 * 16;
; #pragma unroll
;             for (int ks = 0; ks < 4; ++ks) Cf[ks] = *(const LAS bf16x8*)(cbase + ks * 64);
;             LAS unsigned char* hbase = Hs + l15 * BS + q4 * 16;
; #pragma unroll
;             for (int pt = 0; pt < 4; ++pt)
; #pragma unroll
;                 for (int ks = 0; ks < 4; ++ks) { const bf16x8 Hf = *(const LAS bf16x8*)(hbase + pt * 16 * BS + ks * 64); Y[pt] = mfma16(Hf, Cf[ks], Y[pt]); }
.Lssd_late_pf:
	s_add_i32 s33, s33, 0x1e800
	v_lshl_add_u32 v2, v223, 2, s33
	ds_read_b32 v105, v2
.Lssd_yoff:
	ds_read_b128 v[88:91], v239
	ds_read_b128 v[84:87], v239 offset:64
	ds_read_b128 v[80:83], v239 offset:128
	ds_read_b128 v[72:75], v239 offset:192
	ds_read_b128 v[76:79], v240
	ds_read_b128 v[92:95], v240 offset:64
	ds_read_b128 v[96:99], v240 offset:4416
	s_waitcnt lgkmcnt(0)
	v_mfma_f32_16x16x32_bf16 v[76:79], v[76:79], v[88:91], 0
	ds_read_b128 v[100:103], v240 offset:8768
	ds_read_b128 v[154:157], v240 offset:13120
	v_mfma_f32_16x16x32_bf16 v[76:79], v[92:95], v[84:87], v[76:79]
	ds_read_b128 v[92:95], v240 offset:128
	s_waitcnt lgkmcnt(0)
	v_mfma_f32_16x16x32_bf16 v[76:79], v[92:95], v[80:83], v[76:79]
	ds_read_b128 v[92:95], v240 offset:192
	s_waitcnt lgkmcnt(0)
	v_mfma_f32_16x16x32_bf16 v[76:79], v[92:95], v[72:75], v[76:79]
	ds_read_b128 v[92:95], v240 offset:4352
	s_waitcnt lgkmcnt(0)
	v_mfma_f32_16x16x32_bf16 v[92:95], v[92:95], v[88:91], 0
	v_mfma_f32_16x16x32_bf16 v[92:95], v[96:99], v[84:87], v[92:95]
	ds_read_b128 v[96:99], v240 offset:4480
	s_waitcnt lgkmcnt(0)
	v_mfma_f32_16x16x32_bf16 v[92:95], v[96:99], v[80:83], v[92:95]
	ds_read_b128 v[96:99], v240 offset:4544
	s_waitcnt lgkmcnt(0)
	v_mfma_f32_16x16x32_bf16 v[92:95], v[96:99], v[72:75], v[92:95]
	ds_read_b128 v[96:99], v240 offset:8704
	s_waitcnt lgkmcnt(0)
	v_mfma_f32_16x16x32_bf16 v[96:99], v[96:99], v[88:91], 0
	v_mfma_f32_16x16x32_bf16 v[96:99], v[100:103], v[84:87], v[96:99]
	ds_read_b128 v[100:103], v240 offset:8832
	s_waitcnt lgkmcnt(0)
	v_mfma_f32_16x16x32_bf16 v[96:99], v[100:103], v[80:83], v[96:99]
	ds_read_b128 v[100:103], v240 offset:8896
	s_waitcnt lgkmcnt(0)
	v_mfma_f32_16x16x32_bf16 v[96:99], v[100:103], v[72:75], v[96:99]
	ds_read_b128 v[100:103], v240 offset:13056
	s_waitcnt lgkmcnt(0)
	v_mfma_f32_16x16x32_bf16 v[100:103], v[100:103], v[88:91], 0
	v_mfma_f32_16x16x32_bf16 v[100:103], v[154:157], v[84:87], v[100:103]
	ds_read_b128 v[154:157], v240 offset:13184
	s_waitcnt lgkmcnt(0)
	v_mfma_f32_16x16x32_bf16 v[100:103], v[154:157], v[80:83], v[100:103]
	ds_read_b128 v[154:157], v240 offset:13248
	s_waitcnt lgkmcnt(0)
	v_mfma_f32_16x16x32_bf16 v[100:103], v[154:157], v[72:75], v[100:103]
	s_cmp_lt_u32 s83, 0x100
	s_cbranch_scc1 .Lssd_g_start
	s_and_b64 vcc, exec, s[18:19]
	s_cbranch_vccnz .Lssd_zb
	v_add_u32_e32 v2, s95, v234
	v_add_u32_e32 v4, 0x7d, v2
	v_mov_b64_e32 v[20:21], s[66:67]
	v_mad_i64_i32 v[4:5], s[48:49], v4, s69, v[20:21]
	v_mov_b32_e32 v107, v3
	v_lshl_add_u64 v[4:5], v[4:5], 0, v[106:107]
	v_add_u32_e32 v6, 0x7e, v2
	v_add_co_u32_e32 v4, vcc, 0x4000, v4
	v_mad_i64_i32 v[6:7], s[48:49], v6, s69, v[20:21]
	s_nop 0
	v_addc_co_u32_e32 v5, vcc, 0, v5, vcc
	v_lshl_add_u64 v[6:7], v[6:7], 0, v[106:107]
	v_add_u32_e32 v12, 0x7f, v2
	v_add_co_u32_e32 v6, vcc, 0x4000, v6
	v_mad_i64_i32 v[12:13], s[48:49], v12, s69, v[20:21]
	s_nop 0
	v_addc_co_u32_e32 v7, vcc, 0, v7, vcc
	v_lshl_add_u64 v[12:13], v[12:13], 0, v[106:107]
	v_add_u32_e32 v14, 0x80, v2
	v_add_co_u32_e32 v12, vcc, 0x4000, v12
	v_mad_i64_i32 v[14:15], s[48:49], v14, s69, v[20:21]
	s_nop 0
	v_addc_co_u32_e32 v13, vcc, 0, v13, vcc
	v_lshl_add_u64 v[14:15], v[14:15], 0, v[106:107]
	v_add_u32_e32 v2, 0x81, v2
	v_add_co_u32_e32 v16, vcc, 0x4000, v14
	v_mad_i64_i32 v[20:21], s[48:49], v2, s69, v[20:21]
	s_nop 0
	v_addc_co_u32_e32 v17, vcc, 0, v15, vcc
	v_lshl_add_u64 v[20:21], v[20:21], 0, v[106:107]
	v_add_co_u32_e32 v20, vcc, 0x4000, v20
	global_load_dwordx4 v[8:11], v[4:5], off offset:1024
	s_nop 0
	global_load_dwordx4 v[4:7], v[6:7], off offset:1024
	v_addc_co_u32_e32 v21, vcc, 0, v21, vcc
	global_load_dwordx4 v[12:15], v[12:13], off offset:1024
	s_nop 0
	global_load_dwordx4 v[16:19], v[16:17], off offset:1024
	global_load_dwordx4 v[20:23], v[20:21], off offset:1024

; #define LAS __attribute__((address_space(3)))
; __device__ __forceinline__ f32x4 mfma16(bf16x8 a, bf16x8 b, f32x4 c) { return __builtin_amdgcn_mfma_f32_16x16x32_bf16(a, b, c, 0, 0, 0); }
; template <int VAR, bool SIDE> ...
;     ...
;             for (int e = 0; e < 4; ++e) penv[e] = (4 * q4 + e <= l15) ? 0.f : 1e30f;
;             LAS unsigned char* bbase = Bm + l15 * BS + q4 * 16;
; #pragma unroll
;             for (int st = 0; st < 8; ++st) { Gt[st] = (f32x4){0.f, 0.f, 0.f, 0.f};
;                 if (st <= lt) {
; #pragma unroll
;                     for (int ks = 0; ks < 4; ++ks) { const bf16x8 Bf = *(const LAS bf16x8*)(bbase + st * 16 * BS + ks * 64); Gt[st] = mfma16(Bf, Cf[ks], Gt[st]); }
;                     const f32x4 as = *(const LAS f32x4*)(acum + 16 * st + 4 * q4), ds = *(const LAS f32x4*)(dtv + 16 * st + 4 * q4);
; #pragma unroll
;                     for (int e = 0; e < 1; ++e) { const float flagf = (st == lt) ? 1.0f : 0.0f;
;                         const f32x4 dv = (acl - as) - penv * flagf;
;                         f32x4 fv; fv[0] = __builtin_amdgcn_exp2f(dv[0]); fv[1] = __builtin_amdgcn_exp2f(dv[1]); fv[2] = __builtin_amdgcn_exp2f(dv[2]); fv[3] = __builtin_amdgcn_exp2f(dv[3]);
;                         Gt[st] = Gt[st] * (fv * ds); }
;                 } }
.Lssd_g_start:
	v_lshl_add_u32 v107, v108, 2, s33
	v_add_u32_e32 v2, s46, v226
	v_mov_b32_e32 v158, 0
	v_mov_b32_e32 v159, 0
	v_mov_b32_e32 v156, 0
	v_mov_b32_e32 v157, 0
	s_andn2_b64 vcc, exec, s[4:5]
	s_cbranch_vccnz .Lssd_g_done
	ds_read_b128 v[24:27], v224 offset:36864
	ds_read_b128 v[28:31], v224 offset:36928
	ds_read_b128 v[32:35], v224 offset:36992
	ds_read_b128 v[36:39], v224 offset:37056
	ds_read_b128 v[40:43], v107
	ds_read_b128 v[44:47], v2
	s_waitcnt lgkmcnt(5)
	v_mfma_f32_16x16x32_bf16 v[48:51], v[24:27], v[88:91], 0
	s_waitcnt lgkmcnt(4)
	v_mfma_f32_16x16x32_bf16 v[48:51], v[28:31], v[84:87], v[48:51]
	s_waitcnt lgkmcnt(3)
	v_mfma_f32_16x16x32_bf16 v[48:51], v[32:35], v[80:83], v[48:51]
	s_waitcnt lgkmcnt(2)
	v_mfma_f32_16x16x32_bf16 v[48:51], v[36:39], v[72:75], v[48:51]
	s_waitcnt lgkmcnt(0)
	v_sub_f32_e32 v52, v105, v40
	v_sub_f32_e32 v53, v105, v41
	v_sub_f32_e32 v54, v105, v42
	v_sub_f32_e32 v55, v105, v43
	v_sub_f32_e32 v52, v52, v112
	v_sub_f32_e32 v53, v53, v113
	v_sub_f32_e32 v54, v54, v114
	v_sub_f32_e32 v55, v55, v115
	v_exp_f32_e32 v52, v52
	v_exp_f32_e32 v53, v53
	v_exp_f32_e32 v54, v54
	v_exp_f32_e32 v55, v55
	s_nop 0
	v_pk_mul_f32 v[52:53], v[44:45], v[52:53]
	v_pk_mul_f32 v[54:55], v[46:47], v[54:55]
	s_nop 0
	v_pk_mul_f32 v[158:159], v[48:49], v[52:53]
	v_pk_mul_f32 v[156:157], v[50:51], v[54:55]
	v_mov_b32_e32 v166, 0
	v_mov_b32_e32 v167, 0
	v_mov_b32_e32 v164, 0
	v_mov_b32_e32 v165, 0
	s_andn2_b64 vcc, exec, s[74:75]
	s_cbranch_vccnz .Lssd_g_done
	ds_read_b128 v[24:27], v224 offset:41216
	ds_read_b128 v[28:31], v224 offset:41280
	ds_read_b128 v[32:35], v224 offset:41344
	ds_read_b128 v[36:39], v224 offset:41408
	ds_read_b128 v[40:43], v107 offset:64
	ds_read_b128 v[44:47], v2 offset:64
	s_waitcnt lgkmcnt(5)
	v_mfma_f32_16x16x32_bf16 v[48:51], v[24:27], v[88:91], 0
	s_waitcnt lgkmcnt(4)
	v_mfma_f32_16x16x32_bf16 v[48:51], v[28:31], v[84:87], v[48:51]
	s_waitcnt lgkmcnt(3)
	v_mfma_f32_16x16x32_bf16 v[48:51], v[32:35], v[80:83], v[48:51]
	s_waitcnt lgkmcnt(2)
	v_mfma_f32_16x16x32_bf16 v[48:51], v[36:39], v[72:75], v[48:51]
	s_waitcnt lgkmcnt(0)
	v_sub_f32_e32 v52, v105, v40
	v_sub_f32_e32 v53, v105, v41
	v_sub_f32_e32 v54, v105, v42
	v_sub_f32_e32 v55, v105, v43
	v_sub_f32_e32 v52, v52, v116
	v_sub_f32_e32 v53, v53, v117
	v_sub_f32_e32 v54, v54, v118
	v_sub_f32_e32 v55, v55, v119
	v_exp_f32_e32 v52, v52
	v_exp_f32_e32 v53, v53
	v_exp_f32_e32 v54, v54
	v_exp_f32_e32 v55, v55
	s_nop 0
	v_pk_mul_f32 v[52:53], v[44:45], v[52:53]
	v_pk_mul_f32 v[54:55], v[46:47], v[54:55]
	s_nop 0
	v_pk_mul_f32 v[166:167], v[48:49], v[52:53]
	v_pk_mul_f32 v[164:165], v[50:51], v[54:55]
	v_mov_b32_e32 v154, 0
	v_mov_b32_e32 v155, 0
	v_mov_b32_e32 v162, 0
	v_mov_b32_e32 v163, 0
	s_andn2_b64 vcc, exec, s[22:23]
	s_cbranch_vccnz .Lssd_g_done
	ds_read_b128 v[24:27], v224 offset:45568
	ds_read_b128 v[28:31], v224 offset:45632
	ds_read_b128 v[32:35], v224 offset:45696
	ds_read_b128 v[36:39], v224 offset:45760
	ds_read_b128 v[40:43], v107 offset:128
	ds_read_b128 v[44:47], v2 offset:128
	s_waitcnt lgkmcnt(5)
	v_mfma_f32_16x16x32_bf16 v[48:51], v[24:27], v[88:91], 0
	s_waitcnt lgkmcnt(4)
	v_mfma_f32_16x16x32_bf16 v[48:51], v[28:31], v[84:87], v[48:51]
	s_waitcnt lgkmcnt(3)
	v_mfma_f32_16x16x32_bf16 v[48:51], v[32:35], v[80:83], v[48:51]
	s_waitcnt lgkmcnt(2)
	v_mfma_f32_16x16x32_bf16 v[48:51], v[36:39], v[72:75], v[48:51]
	s_waitcnt lgkmcnt(0)
	v_sub_f32_e32 v52, v105, v40
	v_sub_f32_e32 v53, v105, v41
	v_sub_f32_e32 v54, v105, v42
	v_sub_f32_e32 v55, v105, v43
	v_sub_f32_e32 v52, v52, v120
	v_sub_f32_e32 v53, v53, v121
	v_sub_f32_e32 v54, v54, v122
	v_sub_f32_e32 v55, v55, v123
	v_exp_f32_e32 v52, v52
	v_exp_f32_e32 v53, v53
	v_exp_f32_e32 v54, v54
	v_exp_f32_e32 v55, v55
	s_nop 0
	v_pk_mul_f32 v[52:53], v[44:45], v[52:53]
	v_pk_mul_f32 v[54:55], v[46:47], v[54:55]
	s_nop 0
	v_pk_mul_f32 v[154:155], v[48:49], v[52:53]
	v_pk_mul_f32 v[162:163], v[50:51], v[54:55]
	v_mov_b32_e32 v188, 0
	v_mov_b32_e32 v189, 0
	v_mov_b32_e32 v184, 0
	v_mov_b32_e32 v185, 0
	s_andn2_b64 vcc, exec, s[92:93]
	s_cbranch_vccnz .Lssd_g_done
	ds_read_b128 v[24:27], v224 offset:49920
	ds_read_b128 v[28:31], v224 offset:49984
	ds_read_b128 v[32:35], v224 offset:50048
	ds_read_b128 v[36:39], v224 offset:50112
	ds_read_b128 v[40:43], v107 offset:192
	ds_read_b128 v[44:47], v2 offset:192
	s_waitcnt lgkmcnt(5)
	v_mfma_f32_16x16x32_bf16 v[48:51], v[24:27], v[88:91], 0
	s_waitcnt lgkmcnt(4)
	v_mfma_f32_16x16x32_bf16 v[48:51], v[28:31], v[84:87], v[48:51]
	s_waitcnt lgkmcnt(3)
	v_mfma_f32_16x16x32_bf16 v[48:51], v[32:35], v[80:83], v[48:51]
	s_waitcnt lgkmcnt(2)
	v_mfma_f32_16x16x32_bf16 v[48:51], v[36:39], v[72:75], v[48:51]
	s_waitcnt lgkmcnt(0)
	v_sub_f32_e32 v52, v105, v40
	v_sub_f32_e32 v53, v105, v41
	v_sub_f32_e32 v54, v105, v42
	v_sub_f32_e32 v55, v105, v43
	v_sub_f32_e32 v52, v52, v124
	v_sub_f32_e32 v53, v53, v125
	v_sub_f32_e32 v54, v54, v126
	v_sub_f32_e32 v55, v55, v127
	v_exp_f32_e32 v52, v52
	v_exp_f32_e32 v53, v53
	v_exp_f32_e32 v54, v54
	v_exp_f32_e32 v55, v55
	s_nop 0
	v_pk_mul_f32 v[52:53], v[44:45], v[52:53]
	v_pk_mul_f32 v[54:55], v[46:47], v[54:55]
	s_nop 0
	v_pk_mul_f32 v[188:189], v[48:49], v[52:53]
	v_pk_mul_f32 v[184:185], v[50:51], v[54:55]
	v_mov_b32_e32 v160, 0
	v_mov_b32_e32 v161, 0
	v_mov_b32_e32 v186, 0
	v_mov_b32_e32 v187, 0
	s_andn2_b64 vcc, exec, s[24:25]
	s_cbranch_vccnz .Lssd_g_done
; #define LAS __attribute__((address_space(3)))
; __device__ __forceinline__ f32x4 mfma16(bf16x8 a, bf16x8 b, f32x4 c) { return __builtin_amdgcn_mfma_f32_16x16x32_bf16(a, b, c, 0, 0, 0); }
; template <int VAR, bool SIDE> ...
;     ...
;             for (int st = 0; st < 8; ++st) { Gt[st] = (f32x4){0.f, 0.f, 0.f, 0.f};
;                 if (st <= lt) {
; #pragma unroll
;                     for (int ks = 0; ks < 4; ++ks) { const bf16x8 Bf = *(const LAS bf16x8*)(bbase + st * 16 * BS + ks * 64); Gt[st] = mfma16(Bf, Cf[ks], Gt[st]); }
;                     const f32x4 as = *(const LAS f32x4*)(acum + 16 * st + 4 * q4), ds = *(const LAS f32x4*)(dtv + 16 * st + 4 * q4);
; #pragma unroll
;                     for (int e = 0; e < 1; ++e) { const float flagf = (st == lt) ? 1.0f : 0.0f;
;                         const f32x4 dv = (acl - as) - penv * flagf;
;                         f32x4 fv; fv[0] = __builtin_amdgcn_exp2f(dv[0]); fv[1] = __builtin_amdgcn_exp2f(dv[1]); fv[2] = __builtin_amdgcn_exp2f(dv[2]); fv[3] = __builtin_amdgcn_exp2f(dv[3]);
;                         Gt[st] = Gt[st] * (fv * ds); }
;                 } }
	ds_read_b128 v[24:27], v224 offset:54272
	ds_read_b128 v[28:31], v224 offset:54336
	ds_read_b128 v[32:35], v224 offset:54400
	ds_read_b128 v[36:39], v224 offset:54464
	ds_read_b128 v[40:43], v107 offset:256
	ds_read_b128 v[44:47], v2 offset:256
	s_waitcnt lgkmcnt(5)
	v_mfma_f32_16x16x32_bf16 v[48:51], v[24:27], v[88:91], 0
	s_waitcnt lgkmcnt(4)
	v_mfma_f32_16x16x32_bf16 v[48:51], v[28:31], v[84:87], v[48:51]
	s_waitcnt lgkmcnt(3)
	v_mfma_f32_16x16x32_bf16 v[48:51], v[32:35], v[80:83], v[48:51]
	s_waitcnt lgkmcnt(2)
	v_mfma_f32_16x16x32_bf16 v[48:51], v[36:39], v[72:75], v[48:51]
	s_waitcnt lgkmcnt(0)
	v_sub_f32_e32 v52, v105, v40
	v_sub_f32_e32 v53, v105, v41
	v_sub_f32_e32 v54, v105, v42
	v_sub_f32_e32 v55, v105, v43
	v_sub_f32_e32 v52, v52, v128
	v_sub_f32_e32 v53, v53, v129
	v_sub_f32_e32 v54, v54, v130
	v_sub_f32_e32 v55, v55, v131
	v_exp_f32_e32 v52, v52
	v_exp_f32_e32 v53, v53
	v_exp_f32_e32 v54, v54
	v_exp_f32_e32 v55, v55
	s_nop 0
	v_pk_mul_f32 v[52:53], v[44:45], v[52:53]
	v_pk_mul_f32 v[54:55], v[46:47], v[54:55]
	s_nop 0
	v_pk_mul_f32 v[160:161], v[48:49], v[52:53]
	v_pk_mul_f32 v[186:187], v[50:51], v[54:55]
	v_mov_b32_e32 v194, 0
	v_mov_b32_e32 v195, 0
	v_mov_b32_e32 v192, 0
	v_mov_b32_e32 v193, 0
	s_andn2_b64 vcc, exec, s[96:97]
	s_cbranch_vccnz .Lssd_g_done
	ds_read_b128 v[24:27], v224 offset:58624
	ds_read_b128 v[28:31], v224 offset:58688
	ds_read_b128 v[32:35], v224 offset:58752
	ds_read_b128 v[36:39], v224 offset:58816
	ds_read_b128 v[40:43], v107 offset:320
	ds_read_b128 v[44:47], v2 offset:320
	s_waitcnt lgkmcnt(5)
	v_mfma_f32_16x16x32_bf16 v[48:51], v[24:27], v[88:91], 0
	s_waitcnt lgkmcnt(4)
	v_mfma_f32_16x16x32_bf16 v[48:51], v[28:31], v[84:87], v[48:51]
	s_waitcnt lgkmcnt(3)
	v_mfma_f32_16x16x32_bf16 v[48:51], v[32:35], v[80:83], v[48:51]
	s_waitcnt lgkmcnt(2)
	v_mfma_f32_16x16x32_bf16 v[48:51], v[36:39], v[72:75], v[48:51]
	s_waitcnt lgkmcnt(0)
	v_sub_f32_e32 v52, v105, v40
	v_sub_f32_e32 v53, v105, v41
	v_sub_f32_e32 v54, v105, v42
	v_sub_f32_e32 v55, v105, v43
	v_sub_f32_e32 v52, v52, v132
	v_sub_f32_e32 v53, v53, v133
	v_sub_f32_e32 v54, v54, v134
	v_sub_f32_e32 v55, v55, v135
	v_exp_f32_e32 v52, v52
	v_exp_f32_e32 v53, v53
	v_exp_f32_e32 v54, v54
	v_exp_f32_e32 v55, v55
	s_nop 0
	v_pk_mul_f32 v[52:53], v[44:45], v[52:53]
	v_pk_mul_f32 v[54:55], v[46:47], v[54:55]
	s_nop 0
	v_pk_mul_f32 v[194:195], v[48:49], v[52:53]
	v_pk_mul_f32 v[192:193], v[50:51], v[54:55]
	v_mov_b32_e32 v182, 0
	v_mov_b32_e32 v183, 0
	v_mov_b32_e32 v190, 0
	v_mov_b32_e32 v191, 0
	s_andn2_b64 vcc, exec, s[76:77]
	s_cbranch_vccnz .Lssd_g_done
	ds_read_b128 v[24:27], v224 offset:62976
	ds_read_b128 v[28:31], v224 offset:63040
	ds_read_b128 v[32:35], v224 offset:63104
	ds_read_b128 v[36:39], v224 offset:63168
	ds_read_b128 v[40:43], v107 offset:384
	ds_read_b128 v[44:47], v2 offset:384
	s_waitcnt lgkmcnt(5)
	v_mfma_f32_16x16x32_bf16 v[48:51], v[24:27], v[88:91], 0
	s_waitcnt lgkmcnt(4)
	v_mfma_f32_16x16x32_bf16 v[48:51], v[28:31], v[84:87], v[48:51]
	s_waitcnt lgkmcnt(3)
	v_mfma_f32_16x16x32_bf16 v[48:51], v[32:35], v[80:83], v[48:51]
	s_waitcnt lgkmcnt(2)
	v_mfma_f32_16x16x32_bf16 v[48:51], v[36:39], v[72:75], v[48:51]
	s_waitcnt lgkmcnt(0)
	v_sub_f32_e32 v52, v105, v40
	v_sub_f32_e32 v53, v105, v41
	v_sub_f32_e32 v54, v105, v42
	v_sub_f32_e32 v55, v105, v43
	v_sub_f32_e32 v52, v52, v136
	v_sub_f32_e32 v53, v53, v137
	v_sub_f32_e32 v54, v54, v138
	v_sub_f32_e32 v55, v55, v139
	v_exp_f32_e32 v52, v52
	v_exp_f32_e32 v53, v53
	v_exp_f32_e32 v54, v54
	v_exp_f32_e32 v55, v55
	s_nop 0
	v_pk_mul_f32 v[52:53], v[44:45], v[52:53]
	v_pk_mul_f32 v[54:55], v[46:47], v[54:55]
	s_nop 0
	v_pk_mul_f32 v[182:183], v[48:49], v[52:53]
	v_pk_mul_f32 v[190:191], v[50:51], v[54:55]
	v_mov_b32_e32 v196, 0
	v_mov_b32_e32 v197, 0
	v_mov_b32_e32 v198, 0
	v_mov_b32_e32 v199, 0
	s_andn2_b64 vcc, exec, s[16:17]
	s_cbranch_vccnz .Lssd_g_done
	ds_read_b128 v[24:27], v225 offset:30464
	ds_read_b128 v[28:31], v225 offset:30528
	ds_read_b128 v[32:35], v225 offset:30592
	ds_read_b128 v[36:39], v225 offset:30656
	ds_read_b128 v[40:43], v107 offset:448
	ds_read_b128 v[44:47], v2 offset:448
	s_waitcnt lgkmcnt(5)
	v_mfma_f32_16x16x32_bf16 v[48:51], v[24:27], v[88:91], 0
	s_waitcnt lgkmcnt(4)
	v_mfma_f32_16x16x32_bf16 v[48:51], v[28:31], v[84:87], v[48:51]
	s_waitcnt lgkmcnt(3)
	v_mfma_f32_16x16x32_bf16 v[48:51], v[32:35], v[80:83], v[48:51]
	s_waitcnt lgkmcnt(2)
	v_mfma_f32_16x16x32_bf16 v[48:51], v[36:39], v[72:75], v[48:51]
	s_waitcnt lgkmcnt(0)
	v_sub_f32_e32 v52, v105, v40
	v_sub_f32_e32 v53, v105, v41
	v_sub_f32_e32 v54, v105, v42
	v_sub_f32_e32 v55, v105, v43
	v_sub_f32_e32 v52, v52, v140
	v_sub_f32_e32 v53, v53, v141
	v_sub_f32_e32 v54, v54, v142
	v_sub_f32_e32 v55, v55, v143
	v_exp_f32_e32 v52, v52
	v_exp_f32_e32 v53, v53
	v_exp_f32_e32 v54, v54
	v_exp_f32_e32 v55, v55
	s_nop 0
	v_pk_mul_f32 v[52:53], v[44:45], v[52:53]
	v_pk_mul_f32 v[54:55], v[46:47], v[54:55]
	s_nop 0
	v_pk_mul_f32 v[196:197], v[48:49], v[52:53]
	v_pk_mul_f32 v[198:199], v[50:51], v[54:55]

; __device__ __forceinline__ unsigned cvt_pk_bf16(float lo, float hi) { unsigned r; asm volatile("v_cvt_pk_bf16_f32 %0, %1, %2" : "=v"(r) : "v"(lo), "v"(hi)); return r; }
; __device__ __forceinline__ float bflo(unsigned u) { return __uint_as_float(u << 16); }
; __device__ __forceinline__ float bfhi(unsigned u) { return __uint_as_float(u & 0xffff0000u); }
; #define LAS __attribute__((address_space(3)))
; __device__ __forceinline__ s16x4 ldtr(LAS unsigned char* p) { return __builtin_bit_cast(s16x4, __builtin_amdgcn_ds_read_tr16_b64_v4i16((LAS v4i16_t*)p)); }
; __device__ __forceinline__ bf16x8 cat8(s16x4 lo, s16x4 hi) { return (bf16x8){lo[0], lo[1], lo[2], lo[3], hi[0], hi[1], hi[2], hi[3]}; }
; template <int VAR, bool SIDE> ...
;     ...
;             for (int pt = 0; pt < 4; ++pt) { const int p0 = 16 * pt + 4 * q4;
;                 const u32x2 xv = *(const LAS u32x2*)(Xs + l * XS + p0 * 2);
;                 const f32x4 xf = {bflo(xv.x), bfhi(xv.x), bflo(xv.y), bfhi(xv.y)}, zf = {bflo(zv[pt].x), bfhi(zv[pt].x), bflo(zv[pt].y), bfhi(zv[pt].y)};
;                 const f32x4 yv = (Y[pt] + Dk * xf) * zf;
;                 u32x2 pk; pk.x = cvt_pk_bf16(yv[0], yv[1]); pk.y = cvt_pk_bf16(yv[2], yv[3]); if (!(VAR & 1)) *(u32x2*)(zp + 16 * pt) = pk; else asm volatile("" :: "v"(pk.x), "v"(pk.y)); }
;             __builtin_amdgcn_sched_barrier(0);
;             const float et = __builtin_amdgcn_exp2f(acum[127]);
; #pragma unroll
;             for (int pt = 0; pt < 4; ++pt) hacc[pt] *= et;
;             LAS unsigned char* btbase = Bm + (4 * q4 + (l15 >> 2)) * BS + (16 * wave + 4 * (l15 & 3)) * 2;
;             LAS unsigned char* xwbase = Xw + (4 * q4 + (l15 >> 2)) * XS + (l15 & 3) * 8;
; #pragma unroll
;             for (int kk = 0; kk < 4; ++kk) {
;                 const s16x4 blo = ldtr(btbase + (32 * kk) * BS);
;                 const s16x4 bhi = ldtr(btbase + (32 * kk + 16) * BS);
;                 const bf16x8 Bf = cat8(blo, bhi);
; #pragma unroll
;                 for (int pt = 0; pt < 4; ++pt) {
;                     const s16x4 xlo = ldtr(xwbase + (32 * kk) * XS + pt * 32);
;                     const s16x4 xhi = ldtr(xwbase + (32 * kk + 16) * XS + pt * 32);
;                     hacc[pt] = mfma16(Bf, cat8(xlo, xhi), hacc[pt]); }
;             }
.Lssd_pfdone:
	v_lshlrev_b32_e32 v90, 16, v152
	v_and_b32_e32 v91, 0xffff0000, v152
	v_mov_b32_e32 v105, v104
	v_lshlrev_b32_e32 v94, 16, v153
	s_waitcnt lgkmcnt(0)
	v_lshlrev_b32_e32 v92, 16, v88
	v_and_b32_e32 v93, 0xffff0000, v88
	v_lshlrev_b32_e32 v88, 16, v89
	v_and_b32_e32 v89, 0xffff0000, v89
	v_pk_fma_f32 v[84:85], v[110:111], v[92:93], v[84:85]
	v_and_b32_e32 v95, 0xffff0000, v153
	v_pk_fma_f32 v[86:87], v[104:105], v[88:89], v[86:87]
	v_pk_mul_f32 v[84:85], v[84:85], v[90:91]
	v_pk_mul_f32 v[86:87], v[86:87], v[94:95]
	v_cvt_pk_bf16_f32 v84, v84, v85
	v_lshlrev_b32_e32 v88, 16, v150
	v_cvt_pk_bf16_f32 v85, v86, v87
	global_store_dwordx2 v[144:145], v[84:85], off
	ds_read_b64 v[84:85], v241 offset:32
	v_and_b32_e32 v89, 0xffff0000, v150
	v_lshlrev_b32_e32 v90, 16, v151
	v_and_b32_e32 v91, 0xffff0000, v151
	s_waitcnt lgkmcnt(0)
	v_lshlrev_b32_e32 v86, 16, v84
	v_and_b32_e32 v87, 0xffff0000, v84
	v_lshlrev_b32_e32 v84, 16, v85
	v_and_b32_e32 v85, 0xffff0000, v85
	v_pk_fma_f32 v[80:81], v[110:111], v[86:87], v[80:81]
	v_pk_fma_f32 v[82:83], v[104:105], v[84:85], v[82:83]
	v_pk_mul_f32 v[80:81], v[80:81], v[88:89]
	v_pk_mul_f32 v[82:83], v[82:83], v[90:91]
	v_cvt_pk_bf16_f32 v80, v80, v81
	v_lshlrev_b32_e32 v84, 16, v148
	v_cvt_pk_bf16_f32 v81, v82, v83
	global_store_dwordx2 v[144:145], v[80:81], off offset:32
	ds_read_b64 v[80:81], v241 offset:64
	v_and_b32_e32 v85, 0xffff0000, v148
	v_lshlrev_b32_e32 v86, 16, v149
	v_and_b32_e32 v87, 0xffff0000, v149
	s_waitcnt lgkmcnt(0)
	v_lshlrev_b32_e32 v82, 16, v80
	v_and_b32_e32 v83, 0xffff0000, v80
	v_lshlrev_b32_e32 v80, 16, v81
	v_and_b32_e32 v81, 0xffff0000, v81
	v_pk_fma_f32 v[76:77], v[110:111], v[82:83], v[76:77]
	v_pk_fma_f32 v[78:79], v[104:105], v[80:81], v[78:79]
	v_pk_mul_f32 v[76:77], v[76:77], v[84:85]
	v_pk_mul_f32 v[78:79], v[78:79], v[86:87]
	v_cvt_pk_bf16_f32 v76, v76, v77
	v_lshlrev_b32_e32 v80, 16, v146
	v_cvt_pk_bf16_f32 v77, v78, v79
	global_store_dwordx2 v[144:145], v[76:77], off offset:64
	ds_read_b64 v[76:77], v241 offset:96
	v_and_b32_e32 v81, 0xffff0000, v146
	v_lshlrev_b32_e32 v82, 16, v147
	v_and_b32_e32 v83, 0xffff0000, v147
	s_waitcnt lgkmcnt(0)
	v_lshlrev_b32_e32 v78, 16, v76
	v_and_b32_e32 v79, 0xffff0000, v76
	v_lshlrev_b32_e32 v76, 16, v77
	v_and_b32_e32 v77, 0xffff0000, v77
	v_pk_fma_f32 v[72:73], v[110:111], v[78:79], v[72:73]
	v_pk_fma_f32 v[74:75], v[104:105], v[76:77], v[74:75]
	v_pk_mul_f32 v[72:73], v[72:73], v[80:81]
	v_pk_mul_f32 v[74:75], v[74:75], v[82:83]
	v_cvt_pk_bf16_f32 v72, v72, v73
	s_nop 0
	v_cvt_pk_bf16_f32 v73, v74, v75
	global_store_dwordx2 v[144:145], v[72:73], off offset:96
	v_mov_b32_e32 v72, s33
	ds_read_b32 v72, v72 offset:508
	s_or_b64 s[18:19], s[78:79], s[18:19]
	s_and_b64 vcc, exec, s[18:19]
	s_waitcnt lgkmcnt(0)
	v_exp_f32_e32 v72, v72
	s_nop 0
	v_pk_mul_f32 v[58:59], v[58:59], v[72:73] op_sel_hi:[1,0]
	v_pk_mul_f32 v[56:57], v[56:57], v[72:73] op_sel_hi:[1,0]
	v_pk_mul_f32 v[62:63], v[62:63], v[72:73] op_sel_hi:[1,0]
	v_pk_mul_f32 v[60:61], v[60:61], v[72:73] op_sel_hi:[1,0]
	v_pk_mul_f32 v[66:67], v[66:67], v[72:73] op_sel_hi:[1,0]
	v_pk_mul_f32 v[64:65], v[64:65], v[72:73] op_sel_hi:[1,0]
	v_pk_mul_f32 v[70:71], v[70:71], v[72:73] op_sel_hi:[1,0]
	v_pk_mul_f32 v[68:69], v[68:69], v[72:73] op_sel_hi:[1,0]
	ds_read_b64_tr_b16 v[72:73], v229 offset:36864
	ds_read_b64_tr_b16 v[74:75], v229 offset:41216
	ds_read_b64_tr_b16 v[78:79], v2 offset:20736
	ds_read_b64_tr_b16 v[76:77], v2 offset:18432
	ds_read_b64_tr_b16 v[80:81], v2 offset:18464
	s_waitcnt lgkmcnt(0)
	v_mfma_f32_16x16x32_bf16 v[56:59], v[72:75], v[76:79], v[56:59]
	ds_read_b64_tr_b16 v[82:83], v2 offset:20768
	ds_read_b64_tr_b16 v[76:77], v2 offset:18496
	ds_read_b64_tr_b16 v[78:79], v2 offset:20800
	s_waitcnt lgkmcnt(0)
	v_mfma_f32_16x16x32_bf16 v[64:67], v[72:75], v[76:79], v[64:67]
	ds_read_b64_tr_b16 v[76:77], v2 offset:18528
	ds_read_b64_tr_b16 v[78:79], v2 offset:20832
	v_mfma_f32_16x16x32_bf16 v[60:63], v[72:75], v[80:83], v[60:63]
	s_waitcnt lgkmcnt(0)
	v_mfma_f32_16x16x32_bf16 v[68:71], v[72:75], v[76:79], v[68:71]
	ds_read_b64_tr_b16 v[72:73], v229 offset:45568
	ds_read_b64_tr_b16 v[74:75], v229 offset:49920
	ds_read_b64_tr_b16 v[76:77], v2 offset:23040
	ds_read_b64_tr_b16 v[78:79], v2 offset:25344
	s_waitcnt lgkmcnt(0)
	v_mfma_f32_16x16x32_bf16 v[56:59], v[72:75], v[76:79], v[56:59]
	ds_read_b64_tr_b16 v[76:77], v2 offset:23072
	ds_read_b64_tr_b16 v[78:79], v2 offset:25376
	s_waitcnt lgkmcnt(0)
	v_mfma_f32_16x16x32_bf16 v[60:63], v[72:75], v[76:79], v[60:63]
	ds_read_b64_tr_b16 v[76:77], v2 offset:23104
	ds_read_b64_tr_b16 v[78:79], v2 offset:25408
	s_waitcnt lgkmcnt(0)
	v_mfma_f32_16x16x32_bf16 v[64:67], v[72:75], v[76:79], v[64:67]
	ds_read_b64_tr_b16 v[76:77], v2 offset:23136
	ds_read_b64_tr_b16 v[78:79], v2 offset:25440
	s_waitcnt lgkmcnt(0)
	v_mfma_f32_16x16x32_bf16 v[68:71], v[72:75], v[76:79], v[68:71]
	ds_read_b64_tr_b16 v[72:73], v229 offset:54272
	ds_read_b64_tr_b16 v[74:75], v229 offset:58624
	ds_read_b64_tr_b16 v[76:77], v2 offset:27648
	ds_read_b64_tr_b16 v[78:79], v2 offset:29952
	s_waitcnt lgkmcnt(0)
	v_mfma_f32_16x16x32_bf16 v[56:59], v[72:75], v[76:79], v[56:59]
	ds_read_b64_tr_b16 v[76:77], v2 offset:27680
	ds_read_b64_tr_b16 v[78:79], v2 offset:29984
	s_waitcnt lgkmcnt(0)
	v_mfma_f32_16x16x32_bf16 v[60:63], v[72:75], v[76:79], v[60:63]
	ds_read_b64_tr_b16 v[76:77], v2 offset:27712
	ds_read_b64_tr_b16 v[78:79], v2 offset:30016
	s_waitcnt lgkmcnt(0)
	v_mfma_f32_16x16x32_bf16 v[64:67], v[72:75], v[76:79], v[64:67]
	ds_read_b64_tr_b16 v[76:77], v2 offset:27744
	ds_read_b64_tr_b16 v[78:79], v2 offset:30048
	s_waitcnt lgkmcnt(0)
	v_mfma_f32_16x16x32_bf16 v[68:71], v[72:75], v[76:79], v[68:71]
	ds_read_b64_tr_b16 v[72:73], v229 offset:62976
	ds_read_b64_tr_b16 v[74:75], v230 offset:30464
	ds_read_b64_tr_b16 v[76:77], v2 offset:32256
	ds_read_b64_tr_b16 v[78:79], v2 offset:34560
	s_waitcnt lgkmcnt(0)
	v_mfma_f32_16x16x32_bf16 v[56:59], v[72:75], v[76:79], v[56:59]
	ds_read_b64_tr_b16 v[76:77], v2 offset:32288
	ds_read_b64_tr_b16 v[78:79], v2 offset:34592
	s_waitcnt lgkmcnt(0)
	v_mfma_f32_16x16x32_bf16 v[60:63], v[72:75], v[76:79], v[60:63]
	ds_read_b64_tr_b16 v[76:77], v2 offset:32320
	ds_read_b64_tr_b16 v[78:79], v2 offset:34624
	s_waitcnt lgkmcnt(0)
	v_mfma_f32_16x16x32_bf16 v[64:67], v[72:75], v[76:79], v[64:67]
	ds_read_b64_tr_b16 v[76:77], v2 offset:32352
	ds_read_b64_tr_b16 v[78:79], v2 offset:34656
	s_waitcnt lgkmcnt(0)
	v_mfma_f32_16x16x32_bf16 v[68:71], v[72:75], v[76:79], v[68:71]
	s_cbranch_vccnz .LBB0_410
	v_add_f32_e32 v2, v200, v211
	v_add_f32_e32 v72, v200, v212
	v_mul_f32_e32 v73, 0x3fb8aa3b, v2
	v_mul_f32_e32 v74, 0x3fb8aa3b, v72
	v_exp_f32_e32 v73, v73
	v_exp_f32_e32 v74, v74
	s_nop 0
	v_add_f32_e32 v75, 1.0, v73
	v_add_f32_e32 v76, 1.0, v74
	v_add_f32_e32 v77, -1.0, v75
	v_add_f32_e32 v78, -1.0, v76
	v_log_f32_e32 v75, v75
	v_log_f32_e32 v76, v76
	v_rcp_f32_e32 v79, v77
	v_rcp_f32_e32 v80, v78
	s_nop 0
	v_mul_f32_e32 v75, 0x3f317218, v75
	v_mul_f32_e32 v76, 0x3f317218, v76
	v_mul_f32_e32 v79, v73, v79
	v_mul_f32_e32 v80, v74, v80
	v_mul_f32_e32 v75, v75, v79
	v_mul_f32_e32 v76, v76, v80
	v_cmp_eq_f32_e32 vcc, 0, v77
	s_nop 1
	v_cndmask_b32_e32 v75, v75, v73, vcc
	v_cmp_eq_f32_e32 vcc, 0, v78
	s_nop 1
	v_cndmask_b32_e32 v76, v76, v74, vcc
	v_cmp_lt_f32_e32 vcc, s28, v2
	s_nop 1
	v_cndmask_b32_e32 v2, v75, v2, vcc
	v_cmp_lt_f32_e32 vcc, s28, v72
	s_nop 1
	v_cndmask_b32_e32 v72, v76, v72, vcc
	s_branch .LBB0_409
